# adds: attention unit prologue issues its 8 Q/K row loads together (counted waits) instead of 3 dependent batches
# baseline (speedup 1.0000x reference)
; __device__ __forceinline__ int tid_of(int wave_u) { int t; asm volatile("v_mbcnt_lo_u32_b32 %0, -1, 0\n\tv_mbcnt_hi_u32_b32 %0, -1, %0" : "=v"(t)); return t | (wave_u << 6); }
; __device__ __forceinline__ float bf_lo(unsigned w) { return __uint_as_float(w << 16); }
; __device__ __forceinline__ float bf_hi(unsigned w) { return __uint_as_float(w & 0xffff0000u); }
; __device__ __forceinline__ void attn_unit(const bf16* Hb, const bf16* KD, const bf16* VD, bf16* MIX, int row0, int S, int head, int qb, float lam, const float* dng, float kn0, float kn1, LAS unsigned char* lds, int wave_u) {
;     const int tid_l = tid_of(wave_u);
;     const int tid = tid_l, lane = tid & 63, wid = __builtin_amdgcn_readfirstlane(tid >> 6), r32 = lane & 31, hh = lane >> 5;
;     const int c = wid >> 2, qs = wid & 3;
;     const int q0 = qb * 128 + qs * 32;
;     const float slope2 = __uint_as_float(__builtin_amdgcn_readfirstlane(__float_as_uint(exp2f(-2.f * (float)(head + 1)) * 1.4426950408889634f)));
;     lam = __uint_as_float(__builtin_amdgcn_readfirstlane(__float_as_uint(lam)));
;     bf16x8 qr[4];
;     float mub;
;     float m;
;     {   const bf16* Qp = Hb + (size_t)(row0 + q0 + r32) * LDH + O_DQ + head * 128 + c * 64 + hh * 8;
;         const bf16* Kp = KD + ((size_t)head * M + row0 + q0 + r32) * 128 + c * 64 + hh * 8;
;         float qq = 0.f, dot = 0.f;
; #pragma unroll
;         for (int d0 = 0; d0 < 4; ++d0) { qr[d0] = *(const bf16x8*)(Qp + d0 * 16); const u32x4 qw = __builtin_bit_cast(u32x4, qr[d0]); const u32x4 kw = *(const u32x4*)(Kp + d0 * 16);
; #pragma unroll
;             for (int e = 0; e < 4; ++e) { const float qa = bf_lo(qw[e]), qb_ = bf_hi(qw[e]), ka = bf_lo(kw[e]), kb = bf_hi(kw[e]);
;                 qq = fmaf(qa, qa, qq); qq = fmaf(qb_, qb_, qq); dot = fmaf(qa, ka, dot); dot = fmaf(qb_, kb, dot); } }
.LBB0_624:
	v_readlane_b32 s72, v251, 0
	s_lshl_b32 s1, s1, 5
	v_readlane_b32 s74, v251, 2
	v_readlane_b32 s75, v251, 3
	s_add_u32 s36, s74, s1
	s_addc_u32 s37, s75, 0
	s_lshl_b32 s1, s69, 3
	v_mov_b32_e32 v0, s1
	v_readlane_b32 s1, v251, 16
	global_load_dword v9, v0, s[36:37] offset:256 sc1
	global_load_dword v10, v0, s[36:37] offset:260 sc1
	v_mbcnt_lo_u32_b32 v6, -1, 0
	v_mbcnt_hi_u32_b32 v6, -1, v6
	s_lshl_b32 s46, s35, 7
	v_or_b32_e32 v0, s1, v6
	s_not_b32 s4, s69
	v_readfirstlane_b32 s34, v0
	s_ashr_i32 s2, s34, 6
	s_lshl_b32 s70, s2, 5
	s_and_b32 s71, s70, 0x60
	s_or_b32 s1, s71, s46
	s_lshl_b32 s4, s4, 1
	v_and_b32_e32 v131, 31, v6
	v_ldexp_f32 v0, 1.0, s4
	s_add_i32 s68, s1, s0
	v_readfirstlane_b32 s36, v0
	v_add_u32_e32 v0, s68, v131
	v_mul_u32_u24_e32 v0, 0xc20, v0
	v_readlane_b32 s44, v251, 40
	s_ashr_i32 s72, s34, 8
	v_lshlrev_b32_e32 v0, 1, v0
	v_readlane_b32 s45, v251, 41
	s_lshl_b32 s4, s69, 8
	v_bfe_u32 v8, v6, 5, 1
	v_lshl_add_u64 v[2:3], s[44:45], 0, v[0:1]
	s_lshl_b32 s44, s72, 6
	v_lshl_add_u64 v[2:3], v[2:3], 0, s[4:5]
	s_ashr_i32 s45, s44, 31
	s_lshl_b32 s4, s69, 16
	s_lshl_b64 s[44:45], s[44:45], 1
	s_or_b32 s33, s0, s4
	v_lshl_add_u64 v[2:3], v[2:3], 0, s[44:45]
	v_lshlrev_b32_e32 v0, 4, v8
	s_add_i32 s1, s1, s33
	v_lshl_add_u64 v[4:5], v[2:3], 0, v[0:1]
	v_add_lshl_u32 v2, s1, v131, 8
	v_readlane_b32 s0, v251, 44
	v_mov_b32_e32 v3, v1
	v_readlane_b32 s1, v251, 45
	v_cmp_lt_i32_e32 vcc, v204, v205
	s_cmpk_lt_u32 s34, 0x100
	v_lshl_add_u64 v[2:3], s[0:1], 0, v[2:3]
	v_lshl_add_u64 v[2:3], v[2:3], 0, s[44:45]
	v_lshl_add_u64 v[2:3], v[2:3], 0, v[0:1]
	global_load_dwordx4 v[98:101], v[4:5], off
	global_load_dwordx4 v[12:15], v[2:3], off
	global_load_dwordx4 v[102:105], v[4:5], off offset:32
	global_load_dwordx4 v[160:163], v[2:3], off offset:32
	global_load_dwordx4 v[106:109], v[4:5], off offset:64
	global_load_dwordx4 v[164:167], v[2:3], off offset:64
	global_load_dwordx4 v[110:113], v[4:5], off offset:96
	global_load_dwordx4 v[168:171], v[2:3], off offset:96
	s_cselect_b64 s[34:35], -1, 0
	v_and_b32_e32 v7, 63, v6
	v_readfirstlane_b32 s4, v198
	v_readlane_b32 s73, v251, 1
	v_readlane_b32 s76, v251, 4
	v_readlane_b32 s77, v251, 5
	v_readlane_b32 s78, v251, 6
	v_readlane_b32 s79, v251, 7
	s_waitcnt vmcnt(7)
	v_lshlrev_b32_e32 v11, 16, v98
	s_waitcnt vmcnt(6)
	v_lshlrev_b32_e32 v17, 16, v12
	v_and_b32_e32 v16, 0xffff0000, v98
	v_and_b32_e32 v12, 0xffff0000, v12
	v_fma_f32 v0, v11, v11, 0
	v_fma_f32 v11, v11, v17, 0
	v_fmac_f32_e32 v0, v16, v16
	v_fmac_f32_e32 v11, v16, v12
	v_lshlrev_b32_e32 v12, 16, v99
	v_lshlrev_b32_e32 v17, 16, v13
	v_and_b32_e32 v16, 0xffff0000, v99
	v_and_b32_e32 v13, 0xffff0000, v13
	v_fmac_f32_e32 v0, v12, v12
	v_fmac_f32_e32 v11, v12, v17
	v_fmac_f32_e32 v0, v16, v16
	v_fmac_f32_e32 v11, v16, v13
	v_lshlrev_b32_e32 v12, 16, v100
	v_lshlrev_b32_e32 v16, 16, v14
	v_and_b32_e32 v13, 0xffff0000, v100
	v_and_b32_e32 v14, 0xffff0000, v14
	v_fmac_f32_e32 v0, v12, v12
	v_fmac_f32_e32 v11, v12, v16
	v_fmac_f32_e32 v0, v13, v13
	v_fmac_f32_e32 v11, v13, v14
	v_lshlrev_b32_e32 v12, 16, v101
	v_lshlrev_b32_e32 v14, 16, v15
	v_and_b32_e32 v13, 0xffff0000, v101
	v_and_b32_e32 v15, 0xffff0000, v15
	v_fmac_f32_e32 v0, v12, v12
	v_fmac_f32_e32 v11, v12, v14
	v_fmac_f32_e32 v0, v13, v13
	v_fmac_f32_e32 v11, v13, v15
	s_waitcnt vmcnt(5)
	v_lshlrev_b32_e32 v16, 16, v102
	s_waitcnt vmcnt(4)
	v_lshlrev_b32_e32 v18, 16, v160
	v_and_b32_e32 v17, 0xffff0000, v102
	v_and_b32_e32 v12, 0xffff0000, v160
	v_fmac_f32_e32 v0, v16, v16
	v_fmac_f32_e32 v11, v16, v18
	v_fmac_f32_e32 v0, v17, v17
	v_fmac_f32_e32 v11, v17, v12
	v_lshlrev_b32_e32 v12, 16, v103
	v_lshlrev_b32_e32 v17, 16, v161
	v_and_b32_e32 v16, 0xffff0000, v103
	v_and_b32_e32 v13, 0xffff0000, v161
	v_fmac_f32_e32 v0, v12, v12
	v_fmac_f32_e32 v11, v12, v17
	v_fmac_f32_e32 v0, v16, v16
	v_fmac_f32_e32 v11, v16, v13
	v_lshlrev_b32_e32 v12, 16, v104
	v_lshlrev_b32_e32 v16, 16, v162
	v_and_b32_e32 v13, 0xffff0000, v104
	v_and_b32_e32 v14, 0xffff0000, v162
	v_fmac_f32_e32 v0, v12, v12
	v_fmac_f32_e32 v11, v12, v16
	v_fmac_f32_e32 v0, v13, v13
	v_fmac_f32_e32 v11, v13, v14
	v_lshlrev_b32_e32 v12, 16, v105
	v_lshlrev_b32_e32 v14, 16, v163
	v_and_b32_e32 v13, 0xffff0000, v105
	v_and_b32_e32 v15, 0xffff0000, v163
	v_fmac_f32_e32 v0, v12, v12
	v_fmac_f32_e32 v11, v12, v14
	v_fmac_f32_e32 v0, v13, v13
	v_fmac_f32_e32 v11, v13, v15
	s_nop 0
	s_waitcnt vmcnt(3)
	v_lshlrev_b32_e32 v16, 16, v106
	s_waitcnt vmcnt(2)
; #define LAS __attribute__((address_space(3)))
; __device__ __forceinline__ float bf_lo(unsigned w) { return __uint_as_float(w << 16); }
; __device__ __forceinline__ float bf_hi(unsigned w) { return __uint_as_float(w & 0xffff0000u); }
; __device__ __forceinline__ void attn_unit(const bf16* Hb, const bf16* KD, const bf16* VD, bf16* MIX, int row0, int S, int head, int qb, float lam, const float* dng, float kn0, float kn1, LAS unsigned char* lds, int wave_u) {
;     ...
;         for (int d0 = 0; d0 < 4; ++d0) { qr[d0] = *(const bf16x8*)(Qp + d0 * 16); const u32x4 qw = __builtin_bit_cast(u32x4, qr[d0]); const u32x4 kw = *(const u32x4*)(Kp + d0 * 16);
; #pragma unroll
;             for (int e = 0; e < 4; ++e) { const float qa = bf_lo(qw[e]), qb_ = bf_hi(qw[e]), ka = bf_lo(kw[e]), kb = bf_hi(kw[e]);
;                 qq = fmaf(qa, qa, qq); qq = fmaf(qb_, qb_, qq); dot = fmaf(qa, ka, dot); dot = fmaf(qb_, kb, dot); } }
;         qq += __shfl_xor(qq, 32); dot += __shfl_xor(dot, 32);
;         m = dot;
;         float am = sqrtf(qq) * (c ? kn1 : kn0) * 1.001f + 0.01f, bm = dot;
;         mub = am;
;         float sp = am - dot;
; #pragma unroll
;         for (int o = 1; o < 32; o <<= 1) { am = fmaxf(am, __shfl_xor(am, o)); bm = fminf(bm, __shfl_xor(bm, o)); sp = fmaxf(sp, __shfl_xor(sp, o)); }
;         LAS float* red = (LAS float*)(lds + L_RED);
;         if (lane == 0) { red[wid * 4] = am; red[wid * 4 + 1] = bm; red[wid * 4 + 2] = sp; }
	v_lshlrev_b32_e32 v18, 16, v164
	v_and_b32_e32 v17, 0xffff0000, v106
	v_and_b32_e32 v12, 0xffff0000, v164
	v_fmac_f32_e32 v0, v16, v16
	v_fmac_f32_e32 v11, v16, v18
	v_fmac_f32_e32 v0, v17, v17
	v_fmac_f32_e32 v11, v17, v12
	v_lshlrev_b32_e32 v12, 16, v107
	v_lshlrev_b32_e32 v17, 16, v165
	v_and_b32_e32 v16, 0xffff0000, v107
	v_and_b32_e32 v13, 0xffff0000, v165
	v_fmac_f32_e32 v0, v12, v12
	v_fmac_f32_e32 v11, v12, v17
	v_fmac_f32_e32 v0, v16, v16
	v_fmac_f32_e32 v11, v16, v13
	v_lshlrev_b32_e32 v12, 16, v108
	v_lshlrev_b32_e32 v16, 16, v166
	v_and_b32_e32 v13, 0xffff0000, v108
	v_and_b32_e32 v14, 0xffff0000, v166
	v_fmac_f32_e32 v0, v12, v12
	v_fmac_f32_e32 v11, v12, v16
	v_fmac_f32_e32 v0, v13, v13
	v_fmac_f32_e32 v11, v13, v14
	v_lshlrev_b32_e32 v12, 16, v109
	v_lshlrev_b32_e32 v14, 16, v167
	v_and_b32_e32 v13, 0xffff0000, v109
	v_and_b32_e32 v15, 0xffff0000, v167
	v_fmac_f32_e32 v0, v12, v12
	v_fmac_f32_e32 v11, v12, v14
	v_fmac_f32_e32 v0, v13, v13
	v_fmac_f32_e32 v11, v13, v15
	s_waitcnt vmcnt(1)
	v_lshlrev_b32_e32 v12, 16, v110
	s_waitcnt vmcnt(0)
	v_lshlrev_b32_e32 v14, 16, v168
	v_and_b32_e32 v13, 0xffff0000, v110
	v_and_b32_e32 v2, 0xffff0000, v168
	v_fmac_f32_e32 v0, v12, v12
	v_fmac_f32_e32 v11, v12, v14
	v_fmac_f32_e32 v0, v13, v13
	v_fmac_f32_e32 v11, v13, v2
	v_lshlrev_b32_e32 v2, 16, v111
	v_lshlrev_b32_e32 v13, 16, v169
	v_and_b32_e32 v12, 0xffff0000, v111
	v_and_b32_e32 v3, 0xffff0000, v169
	v_fmac_f32_e32 v0, v2, v2
	v_fmac_f32_e32 v11, v2, v13
	v_fmac_f32_e32 v0, v12, v12
	v_fmac_f32_e32 v11, v12, v3
	v_lshlrev_b32_e32 v2, 16, v112
	v_lshlrev_b32_e32 v12, 16, v170
	v_and_b32_e32 v3, 0xffff0000, v112
	v_and_b32_e32 v4, 0xffff0000, v170
	v_fmac_f32_e32 v0, v2, v2
	v_fmac_f32_e32 v11, v2, v12
	v_fmac_f32_e32 v0, v3, v3
	v_fmac_f32_e32 v11, v3, v4
	v_lshlrev_b32_e32 v2, 16, v113
	v_lshlrev_b32_e32 v4, 16, v171
	v_and_b32_e32 v3, 0xffff0000, v113
	v_fmac_f32_e32 v0, v2, v2
	v_fmac_f32_e32 v11, v2, v4
	v_cndmask_b32_e32 v2, v200, v204, vcc
	v_fmac_f32_e32 v0, v3, v3
	v_lshlrev_b32_e32 v208, 2, v2
	ds_bpermute_b32 v2, v208, v0
	v_and_b32_e32 v5, 0xffff0000, v171
	v_fmac_f32_e32 v11, v3, v5
	s_waitcnt lgkmcnt(0)
	v_add_f32_e32 v0, v0, v2
	ds_bpermute_b32 v2, v208, v11
	v_cmp_gt_f32_e32 vcc, s50, v0
	s_waitcnt lgkmcnt(0)
	v_add_f32_e32 v130, v11, v2
	v_mul_f32_e32 v2, 0x4f800000, v0
	v_cndmask_b32_e32 v0, v0, v2, vcc
	v_sqrt_f32_e32 v2, v0
	s_nop 0
	v_add_u32_e32 v3, -1, v2
	v_fma_f32 v4, -v3, v2, v0
	v_cmp_ge_f32_e64 s[0:1], 0, v4
	v_add_u32_e32 v4, 1, v2
	s_nop 0
	v_cndmask_b32_e64 v3, v2, v3, s[0:1]
	v_fma_f32 v2, -v4, v2, v0
	v_cmp_lt_f32_e64 s[0:1], 0, v2
	s_nop 1
	v_cndmask_b32_e64 v2, v3, v4, s[0:1]
	v_mul_f32_e32 v3, 0x37800000, v2
	v_cndmask_b32_e32 v2, v2, v3, vcc
	v_cmp_class_f32_e32 vcc, v0, v201
	s_nop 1
	v_cndmask_b32_e32 v0, v2, v0, vcc
	v_cndmask_b32_e64 v2, v10, v9, s[34:35]
	v_mul_f32_e32 v0, v0, v2
	v_cmp_lt_i32_e32 vcc, v206, v205
	v_fmamk_f32 v209, v0, 0x3f8020c5, v202
	v_sub_f32_e32 v0, v209, v130
	v_cndmask_b32_e32 v2, v200, v206, vcc
	v_lshlrev_b32_e32 v2, 2, v2
	ds_bpermute_b32 v3, v2, v209
	ds_bpermute_b32 v4, v2, v130
	ds_bpermute_b32 v2, v2, v0
	s_waitcnt lgkmcnt(2)
	v_max_f32_e32 v3, v3, v3
	v_max_f32_e32 v3, v209, v3
	s_waitcnt lgkmcnt(0)
	v_max_f32_e32 v2, v2, v2
	v_max_f32_e32 v0, v0, v2
	v_xor_b32_e32 v2, 2, v200
	v_cmp_lt_i32_e32 vcc, v2, v205
	v_max_f32_e32 v4, v4, v4
	v_min_f32_e32 v4, v130, v4
	v_cndmask_b32_e32 v2, v200, v2, vcc
	v_lshlrev_b32_e32 v2, 2, v2
	ds_bpermute_b32 v5, v2, v3
	s_waitcnt lgkmcnt(0)
	v_max_f32_e32 v5, v5, v5
	v_max_f32_e32 v3, v3, v5
	ds_bpermute_b32 v5, v2, v4
	ds_bpermute_b32 v2, v2, v0
	s_waitcnt lgkmcnt(1)
	v_max_f32_e32 v5, v5, v5
	s_waitcnt lgkmcnt(0)
	v_max_f32_e32 v2, v2, v2
	v_max_f32_e32 v0, v0, v2
	v_xor_b32_e32 v2, 4, v200
	v_cmp_lt_i32_e32 vcc, v2, v205
	v_min_f32_e32 v4, v4, v5
	s_nop 0
	v_cndmask_b32_e32 v2, v200, v2, vcc
	v_lshlrev_b32_e32 v2, 2, v2
	ds_bpermute_b32 v5, v2, v3
	s_waitcnt lgkmcnt(0)
	v_max_f32_e32 v5, v5, v5
	v_max_f32_e32 v3, v3, v5
	ds_bpermute_b32 v5, v2, v4
	ds_bpermute_b32 v2, v2, v0
	s_waitcnt lgkmcnt(1)
	v_max_f32_e32 v5, v5, v5
	s_waitcnt lgkmcnt(0)
	v_max_f32_e32 v2, v2, v2
	v_min_f32_e32 v4, v4, v5
	v_max_f32_e32 v5, v0, v2
	v_xor_b32_e32 v0, 8, v200
	v_cmp_lt_i32_e32 vcc, v0, v205
	s_nop 1
	v_cndmask_b32_e32 v0, v200, v0, vcc
	v_lshlrev_b32_e32 v9, 2, v0
	ds_bpermute_b32 v0, v9, v3
	ds_bpermute_b32 v2, v9, v4
	s_waitcnt lgkmcnt(1)
	v_max_f32_e32 v0, v0, v0
	v_max_f32_e32 v0, v3, v0
	ds_bpermute_b32 v3, v9, v5
	s_waitcnt lgkmcnt(1)
	v_max_f32_e32 v2, v2, v2
	v_min_f32_e32 v2, v4, v2
	v_xor_b32_e32 v4, 16, v200
	v_cmp_lt_i32_e32 vcc, v4, v205
	s_waitcnt lgkmcnt(0)
	v_max_f32_e32 v3, v3, v3
	v_max_f32_e32 v3, v5, v3
	v_cndmask_b32_e32 v4, v200, v4, vcc
	v_lshlrev_b32_e32 v9, 2, v4
	ds_bpermute_b32 v4, v9, v0
	ds_bpermute_b32 v5, v9, v2
	ds_bpermute_b32 v9, v9, v3
	v_cmp_eq_u32_e32 vcc, 0, v7
	s_and_saveexec_b64 s[0:1], vcc
	s_cbranch_execz .LBB0_626
	s_waitcnt lgkmcnt(0)
	v_max_f32_e32 v9, v9, v9
	v_max_f32_e32 v3, v3, v3
	s_lshl_b32 s37, s2, 4
	v_max_f32_e32 v12, v3, v9
	v_max_f32_e32 v3, v5, v5
	v_max_f32_e32 v2, v2, v2
	s_add_i32 s37, s37, 0
	v_min_f32_e32 v11, v2, v3
	v_max_f32_e32 v2, v4, v4
	v_max_f32_e32 v0, v0, v0
	s_add_i32 s37, s37, 0x20000
	v_max_f32_e32 v10, v0, v2
	v_mov_b32_e32 v0, s37
	ds_write_b96 v0, v[10:12]
